# mlstm_seq: gate loads and y stores 16 rows x 64 B per instruction (v_permlane16_swap on top of permlane32)
# speedup vs baseline: 1.0612x; 1.0068x over previous
; __device__ __forceinline__ void ffn_conv_item(int tid_in, int b, int strip, bf16_t* h1, const bf16_t* h2, const float* cw, const float* cb, bool st = true) {
;     ...
;     for (int blk = 0; blk < 16; ++blk) {
;         u32x4 ng4[4], nv4[4];
;         if (blk + 1 < 16) {
; #pragma unroll
;             for (int j = 0; j < 4; ++j) { const size_t o_ = off0 + (size_t)(32 * (blk + 1) + 8 * j + rl) * 5632; ng4[j] = __builtin_nontemporal_load((const u32x4*)(h1 + o_)); nv4[j] = __builtin_nontemporal_load((const u32x4*)(h2 + o_)); }
;         }
.LBB0_25:
	s_waitcnt vmcnt(1)
	v_mov_b64_e32 v[48:49], v[36:37]
	v_mov_b64_e32 v[46:47], v[34:35]
	s_cmp_eq_u32 s34, 0x528000
	v_lshl_add_u64 v[140:141], v[138:139], 0, s[34:35]
	s_cbranch_scc1 .LBB0_24
	v_add_co_u32_e32 v34, vcc, 0x4a58000, v140
	s_nop 1
	v_addc_co_u32_e32 v35, vcc, 0, v141, vcc
	v_add_co_u32_e32 v36, vcc, 0xfa58000, v140
	s_nop 1
	v_addc_co_u32_e32 v37, vcc, 0, v141, vcc
	global_load_dwordx4 v[38:41], v[34:35], off nt
	global_load_dwordx4 v[42:45], v[36:37], off nt
	v_add_co_u32_e32 v34, vcc, 0x4a6e000, v140
	s_nop 1
	v_addc_co_u32_e32 v35, vcc, 0, v141, vcc
	v_add_co_u32_e32 v36, vcc, 0xfa6e000, v140
	s_nop 1
	v_addc_co_u32_e32 v37, vcc, 0, v141, vcc
	global_load_dwordx4 v[50:53], v[34:35], off nt
	global_load_dwordx4 v[54:57], v[36:37], off nt
	v_add_co_u32_e32 v34, vcc, 0x4a84000, v140
	s_nop 1
	v_addc_co_u32_e32 v35, vcc, 0, v141, vcc
	v_add_co_u32_e32 v36, vcc, 0xfa84000, v140
	s_nop 1
	v_addc_co_u32_e32 v37, vcc, 0, v141, vcc
	global_load_dwordx4 v[58:61], v[34:35], off nt
	global_load_dwordx4 v[62:65], v[36:37], off nt
	v_add_co_u32_e32 v34, vcc, 0x4a9a000, v140
	s_nop 1
	v_addc_co_u32_e32 v35, vcc, 0, v141, vcc
	v_add_co_u32_e32 v66, vcc, 0xfa9a000, v140
	s_nop 1
	v_addc_co_u32_e32 v67, vcc, 0, v141, vcc
	global_load_dwordx4 v[34:37], v[34:35], off nt
	s_nop 0
	global_load_dwordx4 v[66:69], v[66:67], off nt
	s_branch .LBB0_24
	s_nop 0
	s_nop 0
	s_nop 0
	s_nop 0
	s_nop 0
	s_nop 0
	s_nop 0
	s_nop 0
	s_nop 0
	s_nop 0
	s_nop 0
	s_nop 0
	s_nop 0
	s_nop 0
	s_nop 0
	s_nop 0
	s_nop 0
	s_nop 0
	s_nop 0
	s_nop 0
	s_nop 0
	s_nop 0
	s_nop 0
	s_nop 0
	s_nop 0
	s_nop 0
	s_nop 0
	s_nop 0
	s_nop 0
	s_nop 0
	s_nop 0
	s_nop 0
	s_nop 0
	s_nop 0
	s_nop 0
	s_nop 0
	s_nop 0
	s_nop 0
	s_nop 0
	s_nop 0
	s_nop 0
	s_nop 0
	s_nop 0
	s_nop 0
	s_nop 0
	s_nop 0
	s_nop 0
	s_nop 0
	s_nop 0
	s_nop 0
	s_nop 0
	s_nop 0
	s_nop 0
	s_nop 0
	s_nop 0
	s_nop 0
	s_nop 0
	s_nop 0
	s_nop 0
	s_nop 0
	s_nop 0
	s_nop 0
	s_nop 0
	s_nop 0
	s_nop 0
	s_nop 0
	s_nop 0
	s_nop 0
	s_nop 0
	s_nop 0
	s_nop 0
	s_nop 0
	s_nop 0
	s_nop 0
	s_nop 0
	s_nop 0
	s_nop 0
	s_nop 0
	s_nop 0
	s_nop 0
	s_nop 0
	s_nop 0
	s_nop 0
	s_nop 0
	s_nop 0
	s_nop 0
	s_nop 0
	s_nop 0
	s_nop 0
	s_nop 0
	s_nop 0
	s_nop 0
	s_nop 0
	s_nop 0
	s_nop 0
	s_nop 0
	s_nop 0
	s_nop 0
	s_nop 0
	s_nop 0
	s_nop 0
	s_nop 0
	s_nop 0
	s_nop 0
	s_nop 0
	s_nop 0
	s_nop 0
	s_nop 0
	s_nop 0
	s_nop 0
	s_nop 0
	s_nop 0
	s_nop 0
	s_nop 0
	s_nop 0
	s_nop 0
	s_nop 0
	s_nop 0
	s_nop 0
	s_nop 0
	s_nop 0
	s_nop 0
	s_nop 0
	s_nop 0
	s_nop 0
	s_nop 0
	s_nop 0
	s_nop 0
	s_nop 0
	s_nop 0
	s_nop 0
	s_nop 0
	s_nop 0
	s_nop 0
	s_nop 0
	s_nop 0
	s_nop 0
	s_nop 0
	s_nop 0
	s_nop 0
	s_nop 0
	s_nop 0
	s_nop 0
	s_nop 0
	s_nop 0
	s_nop 0
	s_nop 0
	s_nop 0
	s_nop 0
	s_nop 0
	s_nop 0
	s_nop 0
	s_nop 0
	s_nop 0
	s_nop 0
	s_nop 0
	s_nop 0
	s_nop 0
	s_nop 0
	s_nop 0
	s_nop 0
	s_nop 0
	s_nop 0
	s_nop 0
	s_nop 0
	s_nop 0
	s_nop 0
	s_nop 0
	s_nop 0
	s_nop 0
	s_nop 0
	s_nop 0
	s_nop 0
	s_nop 0
	s_nop 0
	s_nop 0
	s_nop 0
	s_nop 0
	s_nop 0
	s_nop 0
	s_nop 0
	s_nop 0
	s_nop 0
	s_nop 0
	s_nop 0
	s_nop 0
	s_nop 0
	s_nop 0
	s_nop 0
	s_nop 0
	s_nop 0
	s_nop 0
	s_nop 0
	s_nop 0
	s_nop 0
	s_nop 0
	s_nop 0
	s_nop 0
	s_nop 0
	s_nop 0
	s_nop 0
	s_nop 0
	s_nop 0
	s_nop 0
	s_nop 0
	s_nop 0
	s_nop 0
	s_nop 0
	s_nop 0
	s_nop 0
	s_nop 0
	s_nop 0
	s_nop 0
	s_nop 0
	s_nop 0
	s_nop 0
	s_nop 0
	s_nop 0
	s_nop 0
	s_nop 0
	s_nop 0
	s_nop 0
	s_nop 0
	s_nop 0
	s_nop 0
	s_nop 0
	s_nop 0
	s_nop 0
	s_nop 0
	s_nop 0
	s_nop 0
	s_nop 0
	s_nop 0
	s_nop 0
	s_nop 0
	s_nop 0
	s_nop 0
	s_nop 0
	s_nop 0
	s_nop 0
	s_nop 0
	s_nop 0
	s_nop 0
	s_nop 0
	s_nop 0
	s_nop 0
	s_nop 0
	s_nop 0
	s_nop 0
	s_nop 0
	s_nop 0
	s_nop 0
	s_nop 0
	s_nop 0
	s_nop 0
	s_nop 0
	s_nop 0
	s_nop 0
	s_nop 0
	s_nop 0
	s_nop 0
	s_nop 0
	s_nop 0
	s_nop 0
	s_nop 0
	s_nop 0
	s_nop 0
	s_nop 0
	s_nop 0
	s_nop 0
	s_nop 0
	s_nop 0
	s_nop 0
	s_nop 0
	s_nop 0
	s_nop 0
	s_nop 0
	s_nop 0
	s_nop 0
	s_nop 0
	s_nop 0
	s_nop 0
	s_nop 0
	s_nop 0
	s_nop 0
	s_nop 0
	s_nop 0
	s_nop 0
	s_nop 0
	s_nop 0
	s_nop 0
	s_nop 0
	s_nop 0
	s_nop 0
	s_nop 0
	s_nop 0
	s_nop 0
	s_nop 0
	s_nop 0
	s_nop 0
	s_nop 0
	s_nop 0
	s_nop 0
	s_nop 0
	s_nop 0
	s_nop 0
	s_nop 0
	s_nop 0
	s_nop 0
	s_nop 0
	s_nop 0
	s_nop 0
	s_nop 0
	s_nop 0
	s_nop 0
	s_nop 0
	s_nop 0
	s_nop 0
	s_nop 0
	s_nop 0
	s_nop 0
	s_nop 0
	s_nop 0
	s_nop 0
	s_nop 0
	s_nop 0
	s_nop 0
	s_nop 0
	s_nop 0
	s_nop 0
	s_nop 0
	s_nop 0
	s_nop 0
	s_nop 0
	s_nop 0
	s_nop 0
	s_nop 0
	s_nop 0
	s_nop 0
	s_nop 0
	s_nop 0
	s_nop 0
	s_nop 0
	s_nop 0
	s_nop 0
	s_nop 0
	s_nop 0
	s_nop 0
	s_nop 0
	s_nop 0
	s_nop 0
	s_nop 0
	s_nop 0
	s_nop 0
	s_nop 0
	s_nop 0
	s_nop 0
	s_nop 0
	s_nop 0
	s_nop 0
	s_nop 0
	s_nop 0
	s_nop 0
	s_nop 0
	s_nop 0
	s_nop 0
	s_nop 0
	s_nop 0
	s_nop 0
	s_nop 0
	s_nop 0
	s_nop 0
	s_nop 0
	s_nop 0
	s_nop 0
	s_nop 0
	s_nop 0
	s_nop 0
	s_nop 0
	s_nop 0
	s_nop 0
	s_nop 0
	s_nop 0
	s_nop 0
	s_nop 0
	s_nop 0
	s_nop 0
	s_nop 0
	s_nop 0
	s_nop 0
	s_nop 0
	s_nop 0
	s_nop 0
	s_nop 0
	s_nop 0
	s_nop 0
	s_nop 0
	s_nop 0
	s_nop 0
	s_nop 0
	s_nop 0
	s_nop 0
	s_nop 0
	s_nop 0
	s_nop 0
	s_nop 0
	s_nop 0
	s_nop 0
	s_nop 0
	s_nop 0
	s_nop 0
	s_nop 0
	s_nop 0
	s_nop 0
	s_nop 0
	s_nop 0
	s_nop 0
	s_nop 0
	s_nop 0
	s_nop 0
	s_nop 0
	s_nop 0
	s_nop 0
	s_nop 0
	s_nop 0
	s_nop 0
	s_nop 0
	s_nop 0
	s_nop 0
	s_nop 0
	s_nop 0
	s_nop 0
	s_nop 0
	s_nop 0
	s_nop 0
	s_nop 0
	s_nop 0
	s_nop 0
	s_nop 0
	s_nop 0
	s_nop 0
	s_nop 0
	s_nop 0
	s_nop 0
	s_nop 0
	s_nop 0
	s_nop 0
	s_nop 0
	s_nop 0
	s_nop 0
	s_nop 0
	s_nop 0
	s_nop 0
	s_nop 0
	s_nop 0
	s_nop 0
	s_nop 0
	s_nop 0
	s_nop 0
	s_nop 0
	s_nop 0
	s_nop 0
	s_nop 0
	s_nop 0
	s_nop 0
	s_nop 0
	s_nop 0
	s_nop 0
	s_nop 0
	s_nop 0
	s_nop 0
	s_nop 0
	s_nop 0
	s_nop 0
	s_nop 0
	s_nop 0
	s_nop 0
	s_nop 0
	s_nop 0
	s_nop 0
	s_nop 0
	s_nop 0
	s_nop 0
	s_nop 0
	s_nop 0
	s_nop 0
	s_nop 0
	s_nop 0
	s_nop 0
	s_nop 0
	s_nop 0
	s_nop 0
	s_nop 0
	s_nop 0
	s_nop 0
	s_nop 0
	s_nop 0
	s_nop 0
.LBB0_27:
	s_mov_b64 s[12:13], 0
	s_mov_b64 s[16:17], 0
	s_cbranch_execnz .LBB0_95

; #define LAS __attribute__((address_space(3)))
; __device__ __forceinline__ void mlstm_seq(LAS unsigned char* lds, int tid_in, int b, int h, const bf16_t* z1, const bf16_t* z2a, const float* g_hnorm, bf16_t* yb, const unsigned char* ws) {
;     ...
;     ML_PREFETCH(0);
; #pragma nounroll
;     for (int c = 0; c < 64; ++c) {
;         const size_t tok0 = (size_t)b * SEQL + c * 64;
;         const float decay = pdec;
; #pragma unroll
;         for (int i = 0; i < 2; ++i) { *(LAS u32x4*)(Qb + (srow + 32 * i) * QS + sc16 * 16) = pq[i]; *(LAS u32x4*)(KUb + (srow + 32 * i) * US + sc16 * 16) = pk[i]; }
; #pragma unroll
;         for (int i = 0; i < 4; ++i) *(LAS u32x4*)(Vb + (vrow + 16 * i) * VS + vc * 16) = pv[i];
;         *(LAS u32x4*)(SCb + (tid >> 3) * SS + (tid & 7) * 16) = psc;
.Lml_first:
	v_and_b32_e32 v136, 32, v220
	v_mov_b32_e32 v137, 0
	v_lshrrev_b32_e32 v136, 2, v136
	v_lshl_add_u64 v[150:151], v[150:151], 0, v[136:137]
	v_lshl_add_u64 v[168:169], v[168:169], 0, v[136:137]
	v_bfe_u32 v136, v220, 4, 1
	v_mov_b32_e32 v138, 0xfffe0020
	v_sub_u32_e32 v137, 0, v136
	v_mul_lo_u32 v136, v136, v138
	v_lshl_add_u64 v[150:151], v[150:151], 0, v[136:137]
	v_lshl_add_u64 v[168:169], v[168:169], 0, v[136:137]
	v_mov_b32_e32 v250, v134
	v_mov_b32_e32 v251, v135
	ds_write_b128 v0, v[98:101]
	ds_write_b128 v206, v[102:105] offset:17408
	ds_write_b128 v0, v[106:109] offset:8704
	ds_write_b128 v206, v[110:113] offset:27648
	ds_write_b128 v202, v[114:117] offset:37888
	ds_write_b128 v202, v[118:121] offset:47104
	ds_write_b128 v202, v[122:125] offset:56320
	ds_write_b128 v203, v[126:129] offset:27648
	ds_write_b128 v207, v[130:133]
	s_waitcnt lgkmcnt(0)
	s_barrier
.Lml_loop:
	v_add_u32_e32 v144, 0x2000, v208
	ds_read2_b64 v[146:149], v208 offset1:2
	ds_read2_b64 v[222:225], v144 offset0:64 offset1:66
	ds_read2_b64 v[230:233], v208 offset0:4 offset1:6
	ds_read2_b64 v[234:237], v144 offset0:68 offset1:70
	ds_read_b128 v[242:245], v209
	ds_read_b128 v[246:249], v209 offset:16
	ds_read_b128 v[238:241], v165
	s_cmp_eq_u32 s14, 1
	s_cbranch_scc1 .Lml_nopf
	v_lshl_add_u64 v[66:67], s[66:67], 0, v[176:177]
	v_add_co_u32_e32 v68, vcc, 0x6068000, v66
	s_add_u32 s12, s66, s8
	s_nop 0
	v_addc_co_u32_e32 v69, vcc, 0, v67, vcc
	global_load_dwordx4 v[98:101], v[68:69], off offset:2560
	v_add_co_u32_e32 v68, vcc, 0x6069000, v66
	s_addc_u32 s13, s67, s9
	s_nop 0
	v_addc_co_u32_e32 v69, vcc, 0, v67, vcc
	global_load_dwordx4 v[102:105], v[68:69], off offset:512
	v_add_co_u32_e32 v68, vcc, 0x609c000, v66
	global_load_dword v215, v1, s[12:13]
	s_nop 0
	v_addc_co_u32_e32 v69, vcc, 0, v67, vcc
	v_add_co_u32_e32 v66, vcc, 0x609d000, v66
	global_load_dwordx4 v[106:109], v[68:69], off offset:2560
	s_nop 0
	v_addc_co_u32_e32 v67, vcc, 0, v67, vcc
	global_load_dwordx4 v[110:113], v[66:67], off offset:512
	v_lshl_add_u64 v[66:67], s[66:67], 0, v[172:173]
	v_add_co_u32_e32 v68, vcc, 0x10880000, v66
	v_mov_b32_e32 v219, v216
	s_nop 0
	v_addc_co_u32_e32 v69, vcc, 0, v67, vcc
	global_load_dwordx4 v[114:117], v[68:69], off
	v_add_co_u32_e32 v68, vcc, 0x108a0000, v66
	s_nop 1
	v_addc_co_u32_e32 v69, vcc, 0, v67, vcc
	global_load_dwordx4 v[118:121], v[68:69], off
	v_add_co_u32_e32 v68, vcc, 0x108c0000, v66
	s_nop 1
	v_addc_co_u32_e32 v69, vcc, 0, v67, vcc
	v_add_co_u32_e32 v66, vcc, 0x108e0000, v66
	global_load_dwordx4 v[122:125], v[68:69], off
	s_nop 0
	v_addc_co_u32_e32 v67, vcc, 0, v67, vcc
	global_load_dwordx4 v[126:129], v[66:67], off
	v_lshl_add_u64 v[66:67], s[66:67], 0, v[162:163]
	global_load_dwordx4 v[130:133], v[66:67], off
	v_lshl_add_u64 v[66:67], s[66:67], 0, v[150:151]
	s_mov_b64 s[12:13], 0x10881000
	v_lshl_add_u64 v[68:69], v[66:67], 0, s[12:13]
	global_load_dwordx4 v[182:185], v[68:69], off
	s_mov_b64 s[12:13], 0x108a1000
	v_lshl_add_u64 v[68:69], v[66:67], 0, s[12:13]
	global_load_dwordx4 v[186:189], v[68:69], off
	s_mov_b64 s[12:13], 0x108c1000
	v_lshl_add_u64 v[68:69], v[66:67], 0, s[12:13]
	global_load_dwordx4 v[190:193], v[68:69], off
	s_mov_b64 s[12:13], 0x108e1000
	v_lshl_add_u64 v[68:69], v[66:67], 0, s[12:13]
	global_load_dwordx4 v[194:197], v[68:69], off
	v_lshl_add_u64 v[66:67], s[66:67], 0, v[170:171]
	v_add_co_u32_e32 v68, vcc, 0x1dc80000, v66
	s_nop 1
	v_addc_co_u32_e32 v69, vcc, 0, v67, vcc
	v_add_co_u32_e32 v66, vcc, 0x1de80000, v66
	global_load_dword v217, v[68:69], off offset:2048
	s_nop 0
	v_addc_co_u32_e32 v67, vcc, 0, v67, vcc
	global_load_dword v218, v[66:67], off offset:2048
	s_and_saveexec_b64 s[12:13], s[40:41]
	s_cbranch_execz .LBB0_86
	v_lshl_add_u64 v[66:67], s[66:67], 0, v[160:161]
	global_load_dword v219, v[66:67], off

; #define LAS __attribute__((address_space(3)))
; __device__ __forceinline__ float bflo(unsigned w) { return __uint_as_float(w << 16); }
; __device__ __forceinline__ float bfhi(unsigned w) { return __uint_as_float(w & 0xffff0000u); }
; __device__ __forceinline__ unsigned pk2(float lo, float hi) { return pg8::cvt_pk_bf16(lo, hi); }
; #define LDS_WAIT() asm volatile("s_waitcnt lgkmcnt(0)" ::: "memory")
; __device__ __forceinline__ void mlstm_seq(LAS unsigned char* lds, int tid_in, int b, int h, const bf16_t* z1, const bf16_t* z2a, const float* g_hnorm, bf16_t* yb, const unsigned char* ws) {
;     ...
;         LDS_WAIT(); __builtin_amdgcn_s_barrier(); asm volatile("" ::: "memory");
;         if (tid < 128) NV[tid] = decay * NV[tid] + dn;
; #pragma unroll
;         for (int tb = 0; tb < 2; ++tb) {
;             const int t = 32 * tb + r;
;             const float inv = INV[t];
;             const f32x4 pa = *(const LAS f32x4*)(PR + t * 8), pb = *(const LAS f32x4*)(PR + t * 8 + 4);
;             const float rn = inv * rsqrtf(inv * inv * ((pa[0] + pa[1]) + (pa[2] + pa[3]) + (pb[0] + pb[1]) + (pb[2] + pb[3])) * (1.f / 256.f) + EPSN);
; #pragma unroll
;             for (int g = 0; g < 4; ++g) {
;                 const int dv = 32 * wid + 8 * g + 4 * hh;
;                 u32x2 w; w.x = pk2(Z[tb][4 * g] * rn * bflo(zo[tb][g].x), Z[tb][4 * g + 1] * rn * bfhi(zo[tb][g].x));
;                 w.y = pk2(Z[tb][4 * g + 2] * rn * bflo(zo[tb][g].y), Z[tb][4 * g + 3] * rn * bfhi(zo[tb][g].y));
;                 *(u32x2*)(yb + (tok0 + t) * Z2_LD + h * 256 + dv) = w;
.Lml_nvskip:
	s_or_b64 exec, exec, s[12:13]
	v_lshl_add_u64 v[134:135], s[66:67], 0, v[168:169]
	s_add_u32 s8, s8, 4
	s_addc_u32 s9, s9, 0
	s_mov_b64 s[12:13], 0x10800000
	s_mov_b64 s[16:17], 0x10820000
	v_lshl_add_u64 v[136:137], v[134:135], 0, s[12:13]
	v_lshl_add_u64 v[138:139], v[134:135], 0, s[16:17]
	s_mov_b64 s[12:13], 0x10840000
	s_mov_b64 s[16:17], 0x10860000
	v_lshl_add_u64 v[148:149], v[134:135], 0, s[12:13]
	v_lshl_add_u64 v[134:135], v[134:135], 0, s[16:17]
	s_mov_b64 s[16:17], 0x800
	s_waitcnt lgkmcnt(0)
	s_cmp_eq_u32 s14, 1
	s_cbranch_scc1 .Lml_nostage
	s_waitcnt vmcnt(6)
	ds_write_b128 v0, v[98:101]
	ds_write_b128 v206, v[102:105] offset:17408
	ds_write_b128 v0, v[106:109] offset:8704
	ds_write_b128 v206, v[110:113] offset:27648
	ds_write_b128 v202, v[114:117] offset:37888
	ds_write_b128 v202, v[118:121] offset:47104
	ds_write_b128 v202, v[122:125] offset:56320
	ds_write_b128 v203, v[126:129] offset:27648
	ds_write_b128 v207, v[130:133]
.Lml_nostage:
	s_mov_b64 s[12:13], 0x80000
	v_mul_f32_e32 v140, v226, v226
	v_add_f32_e32 v141, v223, v222
	v_add_f32_e32 v142, v224, v225
	v_add_f32_e32 v143, v232, v233
	v_add_f32_e32 v146, v230, v231
	v_add_f32_e32 v141, v141, v142
	v_add_f32_e32 v141, v141, v146
	v_add_f32_e32 v141, v143, v141
	v_mul_f32_e32 v141, v140, v141
	v_fmamk_f32 v141, v141, 0x3b800000, v221
	v_mul_f32_e32 v142, 0x4b800000, v141
	v_cmp_gt_f32_e32 vcc, s77, v141
	s_nop 1
	v_cndmask_b32_e32 v141, v141, v142, vcc
	v_rsq_f32_e32 v141, v141
	s_nop 0
	v_mul_f32_e32 v142, 0x45800000, v141
	v_cndmask_b32_e32 v141, v141, v142, vcc
	v_mul_f32_e32 v145, v226, v141
	v_mul_f32_e32 v82, v82, v145
	v_lshlrev_b32_e32 v140, 16, v180
	v_mul_f32_e32 v83, v83, v145
	v_and_b32_e32 v141, 0xffff0000, v180
	v_mul_f32_e32 v82, v82, v140
	v_mul_f32_e32 v83, v83, v141
	v_mul_f32_e32 v84, v84, v145
	v_lshlrev_b32_e32 v142, 16, v181
	v_mul_f32_e32 v85, v85, v145
	v_and_b32_e32 v143, 0xffff0000, v181
	v_mul_f32_e32 v84, v84, v142
	v_mul_f32_e32 v85, v85, v143
	v_mul_f32_e32 v86, v86, v145
	v_lshlrev_b32_e32 v140, 16, v178
	v_mul_f32_e32 v87, v87, v145
	v_and_b32_e32 v141, 0xffff0000, v178
	v_mul_f32_e32 v86, v86, v140
	v_mul_f32_e32 v87, v87, v141
	v_mul_f32_e32 v88, v88, v145
	v_lshlrev_b32_e32 v142, 16, v179
	v_mul_f32_e32 v89, v89, v145
	v_and_b32_e32 v143, 0xffff0000, v179
	v_mul_f32_e32 v88, v88, v142
	v_mul_f32_e32 v89, v89, v143
	v_cvt_pk_bf16_f32 v82, v82, v83
	v_cvt_pk_bf16_f32 v83, v84, v85
	v_cvt_pk_bf16_f32 v84, v86, v87
	v_cvt_pk_bf16_f32 v85, v88, v89
	s_nop 1
	v_permlane32_swap_b32_e32 v82, v84
	v_permlane32_swap_b32_e32 v83, v85
	v_mul_f32_e32 v90, v90, v145
	v_lshlrev_b32_e32 v140, 16, v174
	v_mul_f32_e32 v91, v91, v145
	v_and_b32_e32 v141, 0xffff0000, v174
	v_mul_f32_e32 v90, v90, v140
	v_mul_f32_e32 v91, v91, v141
	v_mul_f32_e32 v92, v92, v145
	v_lshlrev_b32_e32 v142, 16, v175
	v_mul_f32_e32 v93, v93, v145
	v_and_b32_e32 v143, 0xffff0000, v175
	v_mul_f32_e32 v92, v92, v142
	v_mul_f32_e32 v93, v93, v143
	v_mul_f32_e32 v94, v94, v145
	v_lshlrev_b32_e32 v140, 16, v166
	v_mul_f32_e32 v95, v95, v145
	v_and_b32_e32 v141, 0xffff0000, v166
	v_mul_f32_e32 v94, v94, v140
	v_mul_f32_e32 v95, v95, v141
	v_mul_f32_e32 v96, v96, v145
	v_lshlrev_b32_e32 v142, 16, v167
	v_mul_f32_e32 v97, v97, v145
	v_and_b32_e32 v143, 0xffff0000, v167
	v_mul_f32_e32 v96, v96, v142
	v_mul_f32_e32 v97, v97, v143
	v_cvt_pk_bf16_f32 v90, v90, v91
	v_cvt_pk_bf16_f32 v91, v92, v93
	v_cvt_pk_bf16_f32 v92, v94, v95
	v_cvt_pk_bf16_f32 v93, v96, v97
	s_nop 1
	v_permlane32_swap_b32_e32 v90, v92
	v_permlane32_swap_b32_e32 v91, v93
	s_nop 0
	v_permlane16_swap_b32_e32 v82, v90
	v_permlane16_swap_b32_e32 v83, v91
	v_permlane16_swap_b32_e32 v84, v92
	v_permlane16_swap_b32_e32 v85, v93
	global_store_dwordx4 v[136:137], v[82:85], off
	global_store_dwordx4 v[138:139], v[90:93], off
	v_lshl_add_u64 v[150:151], v[150:151], 0, s[12:13]
	v_lshl_add_u64 v[172:173], v[172:173], 0, s[12:13]
	v_lshl_add_u64 v[168:169], v[168:169], 0, s[12:13]
	s_mov_b64 s[12:13], 0x68000
	v_mul_f32_e32 v140, v227, v227
	v_add_f32_e32 v141, v235, v234
	v_add_f32_e32 v142, v236, v237
; #define LAS __attribute__((address_space(3)))
; __device__ __forceinline__ float bflo(unsigned w) { return __uint_as_float(w << 16); }
; __device__ __forceinline__ float bfhi(unsigned w) { return __uint_as_float(w & 0xffff0000u); }
; __device__ __forceinline__ unsigned pk2(float lo, float hi) { return pg8::cvt_pk_bf16(lo, hi); }
; __device__ __forceinline__ void mlstm_seq(LAS unsigned char* lds, int tid_in, int b, int h, const bf16_t* z1, const bf16_t* z2a, const float* g_hnorm, bf16_t* yb, const unsigned char* ws) {
;     ...
;         u32x2 zo[2][4];
; #pragma unroll
;         for (int tb = 0; tb < 2; ++tb)
; #pragma unroll
;             for (int g = 0; g < 4; ++g) zo[tb][g] = pzo[tb][g];
;         const float wi0 = pwi0, wi1 = pwi1, wq = pwq, eq = peq, dq0 = pdq, dn = pdn;
;     ...
;         for (int tb = 0; tb < 2; ++tb) {
;             const int t = 32 * tb + r;
;             const float inv = INV[t];
;             const f32x4 pa = *(const LAS f32x4*)(PR + t * 8), pb = *(const LAS f32x4*)(PR + t * 8 + 4);
;             const float rn = inv * rsqrtf(inv * inv * ((pa[0] + pa[1]) + (pa[2] + pa[3]) + (pb[0] + pb[1]) + (pb[2] + pb[3])) * (1.f / 256.f) + EPSN);
; #pragma unroll
;             for (int g = 0; g < 4; ++g) {
;                 const int dv = 32 * wid + 8 * g + 4 * hh;
;                 u32x2 w; w.x = pk2(Z[tb][4 * g] * rn * bflo(zo[tb][g].x), Z[tb][4 * g + 1] * rn * bfhi(zo[tb][g].x));
;                 w.y = pk2(Z[tb][4 * g + 2] * rn * bflo(zo[tb][g].y), Z[tb][4 * g + 3] * rn * bfhi(zo[tb][g].y));
;                 *(u32x2*)(yb + (tok0 + t) * Z2_LD + h * 256 + dv) = w;
	v_add_f32_e32 v143, v248, v249
	v_add_f32_e32 v146, v246, v247
	v_add_f32_e32 v141, v141, v142
	v_add_f32_e32 v141, v141, v146
	v_add_f32_e32 v141, v143, v141
	v_mul_f32_e32 v141, v140, v141
	v_fmamk_f32 v141, v141, 0x3b800000, v221
	v_mul_f32_e32 v142, 0x4b800000, v141
	v_cmp_gt_f32_e32 vcc, s77, v141
	s_nop 1
	v_cndmask_b32_e32 v141, v141, v142, vcc
	v_rsq_f32_e32 v141, v141
	s_nop 0
	v_mul_f32_e32 v142, 0x45800000, v141
	v_cndmask_b32_e32 v141, v141, v142, vcc
	v_mul_f32_e32 v145, v227, v141
	v_mul_f32_e32 v66, v66, v145
	v_lshlrev_b32_e32 v140, 16, v158
	v_mul_f32_e32 v67, v67, v145
	v_and_b32_e32 v141, 0xffff0000, v158
	v_mul_f32_e32 v66, v66, v140
	v_mul_f32_e32 v67, v67, v141
	v_mul_f32_e32 v68, v68, v145
	v_lshlrev_b32_e32 v142, 16, v159
	v_mul_f32_e32 v69, v69, v145
	v_and_b32_e32 v143, 0xffff0000, v159
	v_mul_f32_e32 v68, v68, v142
	v_mul_f32_e32 v69, v69, v143
	v_mul_f32_e32 v70, v70, v145
	v_lshlrev_b32_e32 v140, 16, v156
	v_mul_f32_e32 v71, v71, v145
	v_and_b32_e32 v141, 0xffff0000, v156
	v_mul_f32_e32 v70, v70, v140
	v_mul_f32_e32 v71, v71, v141
	v_mul_f32_e32 v72, v72, v145
	v_lshlrev_b32_e32 v142, 16, v157
	v_mul_f32_e32 v73, v73, v145
	v_and_b32_e32 v143, 0xffff0000, v157
	v_mul_f32_e32 v72, v72, v142
	v_mul_f32_e32 v73, v73, v143
	v_cvt_pk_bf16_f32 v66, v66, v67
	v_cvt_pk_bf16_f32 v67, v68, v69
	v_cvt_pk_bf16_f32 v68, v70, v71
	v_cvt_pk_bf16_f32 v69, v72, v73
	s_nop 1
	v_permlane32_swap_b32_e32 v66, v68
	v_permlane32_swap_b32_e32 v67, v69
	v_mul_f32_e32 v74, v74, v145
	v_lshlrev_b32_e32 v140, 16, v154
	v_mul_f32_e32 v75, v75, v145
	v_and_b32_e32 v141, 0xffff0000, v154
	v_mul_f32_e32 v74, v74, v140
	v_mul_f32_e32 v75, v75, v141
	v_mul_f32_e32 v76, v76, v145
	v_lshlrev_b32_e32 v142, 16, v155
	v_mul_f32_e32 v77, v77, v145
	v_and_b32_e32 v143, 0xffff0000, v155
	v_mul_f32_e32 v76, v76, v142
	v_mul_f32_e32 v77, v77, v143
	v_mul_f32_e32 v78, v78, v145
	v_lshlrev_b32_e32 v140, 16, v152
	v_mul_f32_e32 v79, v79, v145
	v_and_b32_e32 v141, 0xffff0000, v152
	v_mul_f32_e32 v78, v78, v140
	v_mul_f32_e32 v79, v79, v141
	v_mul_f32_e32 v80, v80, v145
	v_lshlrev_b32_e32 v142, 16, v153
	v_mul_f32_e32 v81, v81, v145
	v_and_b32_e32 v143, 0xffff0000, v153
	v_mul_f32_e32 v80, v80, v142
	v_mul_f32_e32 v81, v81, v143
	v_cvt_pk_bf16_f32 v74, v74, v75
	v_cvt_pk_bf16_f32 v75, v76, v77
	v_cvt_pk_bf16_f32 v76, v78, v79
	v_cvt_pk_bf16_f32 v77, v80, v81
	s_nop 1
	v_permlane32_swap_b32_e32 v74, v76
	v_permlane32_swap_b32_e32 v75, v77
	s_nop 0
	v_permlane16_swap_b32_e32 v66, v74
	v_permlane16_swap_b32_e32 v67, v75
	v_permlane16_swap_b32_e32 v68, v76
	v_permlane16_swap_b32_e32 v69, v77
	global_store_dwordx4 v[148:149], v[66:69], off
	global_store_dwordx4 v[134:135], v[74:77], off
	v_lshl_add_u64 v[160:161], v[160:161], 0, s[92:93]
	v_lshl_add_u64 v[162:163], v[162:163], 0, s[94:95]
	v_lshl_add_u64 v[170:171], v[170:171], 0, s[16:17]
	v_lshl_add_u64 v[176:177], v[176:177], 0, s[12:13]
	s_add_i32 s14, s14, -1
	s_waitcnt vmcnt(4)
	v_permlane16_swap_b32_e32 v182, v186
	v_permlane16_swap_b32_e32 v183, v187
	v_permlane16_swap_b32_e32 v184, v188
	v_permlane16_swap_b32_e32 v185, v189
	v_permlane16_swap_b32_e32 v190, v194
	v_permlane16_swap_b32_e32 v191, v195
	v_permlane16_swap_b32_e32 v192, v196
	v_permlane16_swap_b32_e32 v193, v197
	v_permlane32_swap_b32_e32 v182, v184
	v_permlane32_swap_b32_e32 v183, v185
	v_permlane32_swap_b32_e32 v186, v188
	v_permlane32_swap_b32_e32 v187, v189
	v_permlane32_swap_b32_e32 v190, v192
	v_permlane32_swap_b32_e32 v191, v193
	v_permlane32_swap_b32_e32 v194, v196
	v_permlane32_swap_b32_e32 v195, v197
	v_mov_b64_e32 v[180:181], v[182:183]
	v_mov_b64_e32 v[178:179], v[184:185]
	v_mov_b64_e32 v[174:175], v[186:187]
	v_mov_b64_e32 v[166:167], v[188:189]
	v_mov_b64_e32 v[158:159], v[190:191]
	v_mov_b64_e32 v[156:157], v[192:193]
	v_mov_b64_e32 v[154:155], v[194:195]
	v_mov_b64_e32 v[152:153], v[196:197]
	v_mov_b32_e32 v250, v217
	v_mov_b32_e32 v251, v218
	v_mov_b32_e32 v216, v219
	v_mov_b32_e32 v164, v215
	s_cmp_eq_u32 s14, 0
	s_cbranch_scc1 .LBB0_93
	s_waitcnt lgkmcnt(0)
	s_barrier
	s_branch .Lml_loop
